# W_in bf16 conversion items remapped (8 rows x 8 k-chunks per wave) so each wave writes full 128B lines instead of 16B fragments completed by other XCDs
# speedup vs baseline: 1.0031x; 1.0031x over previous
.LBB0_630:
	v_lshrrev_b32_e32 v0, 6, v6
	v_lshrrev_b32_e32 v1, 5, v0
	s_mov_b32 s10, 0x539782a
	v_mul_hi_u32 v1, v1, s10
	v_mul_u32_u24_e32 v3, 0x620, v1
	v_sub_u32_e32 v0, v0, v3
	v_and_b32_e32 v3, 7, v6
	v_lshl_or_b32 v0, v0, 3, v3
	v_bfe_u32 v3, v6, 3, 3
	v_lshl_or_b32 v1, v1, 3, v3
	s_movk_i32 s10, 0x18ff
	v_cmp_lt_i32_e32 vcc, s10, v0
	s_and_saveexec_b64 s[10:11], vcc
	s_xor_b64 s[10:11], exec, s[10:11]
	s_cbranch_execz .LBB0_640
	s_movk_i32 s12, 0x1cff
	v_cmp_lt_u32_e32 vcc, s12, v0
	s_and_saveexec_b64 s[12:13], vcc
	s_xor_b64 s[12:13], exec, s[12:13]
	s_cbranch_execz .LBB0_637
	s_movk_i32 s14, 0x20ff
	v_cmp_lt_u32_e32 vcc, s14, v0
	s_and_saveexec_b64 s[14:15], vcc
	s_xor_b64 s[14:15], exec, s[14:15]
	v_add_u32_e32 v96, 0xffffff90, v0
	s_andn2_saveexec_b64 s[14:15], s[14:15]
	v_add_u32_e32 v96, 0xfffff310, v0
	s_or_b64 exec, exec, s[14:15]
